# adds: attention softmax VALU trimmed (chunk max via 4 v_max3 on far tiles; bias addresses from one shifted base on selected-block tiles)
# baseline (speedup 1.0000x reference)
; __device__ __forceinline__ void attn_item(const Params& p, unsigned char* lds, int item) {
;     ...
;         for (int ch = 0; ch < 8; ++ch) if (2 * ch < nkt) {
;             f32x4 sA[2], sB[2];
; #pragma unroll
;             for (int k4 = 0; k4 < 2; ++k4) { sA[k4] = (f32x4){0.f, 0.f, 0.f, 0.f}; sB[k4] = (f32x4){0.f, 0.f, 0.f, 0.f};
;                 if (2 * ch + k4 < nkt) { const unsigned char* ka = lds + AT_K + (16 * (2 * ch + k4) + qi) * 272 + 16 * g4;
; #pragma unroll
;                     for (int s = 0; s < 4; ++s) { const bf16x8 a = *(const bf16x8*)(ka + 64 * s);
;                         sA[k4] = __builtin_amdgcn_mfma_f32_16x16x32_bf16(a, bqA[s], sA[k4], 0, 0, 0); sB[k4] = __builtin_amdgcn_mfma_f32_16x16x32_bf16(a, bqB[s], sB[k4], 0, 0, 0); } } }
.LBB0_385:
	ds_read_b128 v[68:71], v214
	ds_read_b128 v[72:75], v214 offset:64
	s_xor_b64 s[12:13], s[12:13], -1
	v_cndmask_b32_e64 v0, 0, 1, s[12:13]
	s_mov_b64 s[18:19], -1
	s_waitcnt lgkmcnt(0)
	v_mfma_f32_16x16x32_bf16 v[76:79], v[68:71], v[64:67], 0
	v_cmp_ne_u32_e64 s[6:7], 1, v0
	s_andn2_b64 vcc, exec, s[12:13]
	v_mfma_f32_16x16x32_bf16 v[68:71], v[68:71], v[56:59], 0
	v_mfma_f32_16x16x32_bf16 v[76:79], v[72:75], v[60:63], v[76:79]
	v_mfma_f32_16x16x32_bf16 v[68:71], v[72:75], v[52:55], v[68:71]
	ds_read_b128 v[72:75], v214 offset:128
	ds_read_b128 v[80:83], v214 offset:192
	s_waitcnt lgkmcnt(1)
	v_mfma_f32_16x16x32_bf16 v[76:79], v[72:75], v[48:51], v[76:79]
	v_mfma_f32_16x16x32_bf16 v[68:71], v[72:75], v[40:43], v[68:71]
	s_waitcnt lgkmcnt(0)
	v_mfma_f32_16x16x32_bf16 v[76:79], v[80:83], v[44:47], v[76:79]
	v_mfma_f32_16x16x32_bf16 v[68:71], v[80:83], v[36:39], v[68:71]
	ds_read_b128 v[72:75], v214 offset:4352
	ds_read_b128 v[80:83], v214 offset:4416
	s_waitcnt lgkmcnt(1)
	v_mfma_f32_16x16x32_bf16 v[84:87], v[72:75], v[64:67], 0
	v_mfma_f32_16x16x32_bf16 v[72:75], v[72:75], v[56:59], 0
	s_waitcnt lgkmcnt(0)
	v_mfma_f32_16x16x32_bf16 v[84:87], v[80:83], v[60:63], v[84:87]
	v_mfma_f32_16x16x32_bf16 v[72:75], v[80:83], v[52:55], v[72:75]
	ds_read_b128 v[80:83], v214 offset:4480
	ds_read_b128 v[92:95], v214 offset:4544
	s_waitcnt lgkmcnt(1)
	v_mfma_f32_16x16x32_bf16 v[84:87], v[80:83], v[48:51], v[84:87]
	v_mfma_f32_16x16x32_bf16 v[72:75], v[80:83], v[40:43], v[72:75]
	s_waitcnt lgkmcnt(0)
	v_mfma_f32_16x16x32_bf16 v[80:83], v[92:95], v[44:47], v[84:87]
	v_mfma_f32_16x16x32_bf16 v[72:75], v[92:95], v[36:39], v[72:75]
	s_cbranch_vccnz .LBB0_387
	v_max3_f32 v0, v76, v77, v78
	v_max3_f32 v0, v0, v79, s95
	v_max3_f32 v2, v80, v81, v82
	v_max3_f32 v91, v0, v2, v83
	s_mov_b64 s[18:19], 0
	v_mov_b32_e32 v89, v83
	v_mov_b32_e32 v88, v82
	v_mov_b32_e32 v87, v81
	v_mov_b32_e32 v86, v80
	v_mov_b32_e32 v85, v79
	v_mov_b32_e32 v84, v78
	v_mov_b32_e32 v3, v77
	v_mov_b32_e32 v2, v76

.LBB0_392:
	v_and_b32_e32 v77, 64, v215
	v_xor_b32_e32 v76, 16, v215
	v_add_u32_e32 v77, 64, v77
	v_cmp_lt_i32_e32 vcc, v76, v77
	v_xor_b32_e32 v79, 32, v215
	v_max_f32_e32 v78, v91, v91
	v_cndmask_b32_e32 v76, v215, v76, vcc
	v_lshlrev_b32_e32 v179, 2, v76
	ds_bpermute_b32 v76, v179, v91
	v_cmp_lt_i32_e32 vcc, v79, v77
	s_xor_b64 s[20:21], s[8:9], -1
	s_mov_b64 s[18:19], -1
	v_cndmask_b32_e32 v77, v215, v79, vcc
	s_waitcnt lgkmcnt(0)
	v_max_f32_e32 v76, v76, v76
	v_max_f32_e32 v76, v78, v76
	v_lshlrev_b32_e32 v238, 2, v77
	ds_bpermute_b32 v77, v238, v76
	s_andn2_b64 vcc, exec, s[20:21]
	s_waitcnt lgkmcnt(0)
	v_max3_f32 v241, v76, v77, s95
	v_sub_f32_e32 v2, v2, v241
	v_exp_f32_e32 v108, v2
	v_sub_f32_e32 v2, v3, v241
	v_exp_f32_e32 v109, v2
	v_sub_f32_e32 v2, v84, v241
	v_exp_f32_e32 v110, v2
	v_sub_f32_e32 v2, v85, v241
	v_exp_f32_e32 v132, v2
	v_sub_f32_e32 v2, v86, v241
	v_exp_f32_e32 v133, v2
	v_sub_f32_e32 v2, v87, v241
	v_exp_f32_e32 v134, v2
	v_sub_f32_e32 v2, v88, v241
	v_exp_f32_e32 v135, v2
	v_sub_f32_e32 v2, v89, v241
	v_exp_f32_e32 v136, v2
	v_cndmask_b32_e64 v2, 0, 1, s[20:21]
	v_cmp_neq_f32_e64 s[10:11], s95, v241
	v_cmp_ne_u32_e64 s[8:9], 1, v2
	v_cvt_pk_bf16_f32 v104, v108, v109
	v_cvt_pk_bf16_f32 v105, v110, v132
	v_cvt_pk_bf16_f32 v106, v133, v134
	v_cvt_pk_bf16_f32 v107, v135, v136
	s_cbranch_vccnz .LBB0_394
	v_max3_f32 v2, v68, v69, v70
	v_max3_f32 v2, v2, v71, s95
	v_max3_f32 v3, v72, v73, v74
	v_max3_f32 v83, v2, v3, v75
	s_mov_b64 s[18:19], 0
	v_mov_b32_e32 v81, v75
	v_mov_b32_e32 v80, v74
	v_mov_b32_e32 v79, v73
	v_mov_b32_e32 v78, v72
	v_mov_b32_e32 v77, v71
	v_mov_b32_e32 v76, v70
	v_mov_b32_e32 v3, v69
	v_mov_b32_e32 v2, v68

.LBB0_397:
	s_andn2_b64 vcc, exec, s[14:15]
	s_cbranch_vccnz .LBB0_399
	s_add_i32 s14, 0, 0x22800
	v_lshl_add_u32 v2, v82, 2, s14
	v_add_u32_e32 v3, -4, v2
	v_add_u32_e32 v76, -8, v2
	v_add_u32_e32 v77, -12, v2
	v_add_u32_e32 v78, 0xffffffc0, v2
	v_subrev_u32_e32 v79, 0x44, v2
	v_subrev_u32_e32 v80, 0x48, v2
	v_subrev_u32_e32 v81, 0x4c, v2
	v_min_u32_e32 v2, 0x247fc, v2
	v_min_u32_e32 v3, 0x247fc, v3
	v_min_u32_e32 v76, 0x247fc, v76
	v_min_u32_e32 v77, 0x247fc, v77
	v_min_u32_e32 v78, 0x247fc, v78
	v_min_u32_e32 v79, 0x247fc, v79
	v_min_u32_e32 v80, 0x247fc, v80
	v_min_u32_e32 v81, 0x247fc, v81
	ds_read_b32 v2, v2
	ds_read_b32 v3, v3
	ds_read_b32 v76, v76
	ds_read_b32 v77, v77
	ds_read_b32 v78, v78
	ds_read_b32 v79, v79
	ds_read_b32 v80, v80
	ds_read_b32 v81, v81
	s_waitcnt lgkmcnt(6)
	v_pk_add_f32 v[2:3], v[68:69], v[2:3]
	s_waitcnt lgkmcnt(4)
	v_pk_add_f32 v[76:77], v[70:71], v[76:77]
	v_max3_f32 v68, v2, s95, v3
	v_max3_f32 v68, v68, v76, v77
	s_waitcnt lgkmcnt(2)
	v_pk_add_f32 v[78:79], v[72:73], v[78:79]
	s_waitcnt lgkmcnt(0)
	v_pk_add_f32 v[80:81], v[74:75], v[80:81]
	v_max3_f32 v68, v68, v78, v79
	v_max3_f32 v83, v68, v80, v81

; __device__ __forceinline__ void attn_item(const Params& p, unsigned char* lds, int item) {
;     ...
;         for (int ch = 0; ch < 8; ++ch) if (2 * ch < nkt) {
;             f32x4 sA[2], sB[2];
; #pragma unroll
;             for (int k4 = 0; k4 < 2; ++k4) { sA[k4] = (f32x4){0.f, 0.f, 0.f, 0.f}; sB[k4] = (f32x4){0.f, 0.f, 0.f, 0.f};
;                 if (2 * ch + k4 < nkt) { const unsigned char* ka = lds + AT_K + (16 * (2 * ch + k4) + qi) * 272 + 16 * g4;
; #pragma unroll
;                     for (int s = 0; s < 4; ++s) { const bf16x8 a = *(const bf16x8*)(ka + 64 * s);
;                         sA[k4] = __builtin_amdgcn_mfma_f32_16x16x32_bf16(a, bqA[s], sA[k4], 0, 0, 0); sB[k4] = __builtin_amdgcn_mfma_f32_16x16x32_bf16(a, bqB[s], sB[k4], 0, 0, 0); } } }
.LBB0_406:
	ds_read_b128 v[132:135], v206 offset:8704
	ds_read_b128 v[136:139], v206 offset:8768
	s_mov_b64 s[14:15], -1
	s_and_b64 vcc, exec, s[6:7]
	s_waitcnt lgkmcnt(1)
	v_mfma_f32_16x16x32_bf16 v[140:143], v[132:135], v[64:67], 0
	v_mfma_f32_16x16x32_bf16 v[132:135], v[132:135], v[56:59], 0
	s_waitcnt lgkmcnt(0)
	v_mfma_f32_16x16x32_bf16 v[140:143], v[136:139], v[60:63], v[140:143]
	v_mfma_f32_16x16x32_bf16 v[132:135], v[136:139], v[52:55], v[132:135]
	ds_read_b128 v[136:139], v206 offset:8832
	ds_read_b128 v[144:147], v206 offset:8896
	s_waitcnt lgkmcnt(1)
	v_mfma_f32_16x16x32_bf16 v[140:143], v[136:139], v[48:51], v[140:143]
	v_mfma_f32_16x16x32_bf16 v[132:135], v[136:139], v[40:43], v[132:135]
	s_waitcnt lgkmcnt(0)
	v_mfma_f32_16x16x32_bf16 v[140:143], v[144:147], v[44:47], v[140:143]
	v_mfma_f32_16x16x32_bf16 v[132:135], v[144:147], v[36:39], v[132:135]
	ds_read_b128 v[136:139], v206 offset:13056
	ds_read_b128 v[144:147], v206 offset:13120
	s_waitcnt lgkmcnt(1)
	v_mfma_f32_16x16x32_bf16 v[188:191], v[136:139], v[64:67], 0
	v_mfma_f32_16x16x32_bf16 v[136:139], v[136:139], v[56:59], 0
	s_waitcnt lgkmcnt(0)
	v_mfma_f32_16x16x32_bf16 v[188:191], v[144:147], v[60:63], v[188:191]
	v_mfma_f32_16x16x32_bf16 v[136:139], v[144:147], v[52:55], v[136:139]
	ds_read_b128 v[144:147], v206 offset:13184
	ds_read_b128 v[244:247], v206 offset:13248
	s_waitcnt lgkmcnt(1)
	v_mfma_f32_16x16x32_bf16 v[188:191], v[144:147], v[48:51], v[188:191]
	v_mfma_f32_16x16x32_bf16 v[136:139], v[144:147], v[40:43], v[136:139]
	s_waitcnt lgkmcnt(0)
	v_mfma_f32_16x16x32_bf16 v[144:147], v[244:247], v[44:47], v[188:191]
	v_mfma_f32_16x16x32_bf16 v[136:139], v[244:247], v[36:39], v[136:139]
	s_cbranch_vccnz .LBB0_408
	v_max3_f32 v2, v140, v141, v142
	v_max3_f32 v2, v2, v143, s95
	v_max3_f32 v3, v144, v145, v146
	v_max3_f32 v243, v2, v3, v147
	s_mov_b64 s[14:15], 0
	v_mov_b32_e32 v193, v147
	v_mov_b32_e32 v192, v146
	v_mov_b32_e32 v191, v145
	v_mov_b32_e32 v190, v144
	v_mov_b32_e32 v189, v143
	v_mov_b32_e32 v188, v142
	v_mov_b32_e32 v3, v141
	v_mov_b32_e32 v2, v140

.LBB0_411:
	s_andn2_b64 vcc, exec, s[14:15]
	s_cbranch_vccnz .LBB0_413
	s_add_i32 s14, 0, 0x22800
	v_lshl_add_u32 v2, v242, 2, s14
	v_add_u32_e32 v3, -4, v2
	v_add_u32_e32 v188, -8, v2
	v_add_u32_e32 v189, -12, v2
	v_add_u32_e32 v190, 0xffffffc0, v2
	v_subrev_u32_e32 v191, 0x44, v2
	v_subrev_u32_e32 v192, 0x48, v2
	v_subrev_u32_e32 v193, 0x4c, v2
	v_min_u32_e32 v2, 0x247fc, v2
	v_min_u32_e32 v3, 0x247fc, v3
	v_min_u32_e32 v188, 0x247fc, v188
	v_min_u32_e32 v189, 0x247fc, v189
	v_min_u32_e32 v190, 0x247fc, v190
	v_min_u32_e32 v191, 0x247fc, v191
	v_min_u32_e32 v192, 0x247fc, v192
	v_min_u32_e32 v193, 0x247fc, v193
	ds_read_b32 v2, v2
	ds_read_b32 v3, v3
	ds_read_b32 v188, v188
	ds_read_b32 v189, v189
	ds_read_b32 v190, v190
	ds_read_b32 v191, v191
	ds_read_b32 v192, v192
	ds_read_b32 v193, v193
	s_waitcnt lgkmcnt(6)
	v_pk_add_f32 v[2:3], v[140:141], v[2:3]
	s_waitcnt lgkmcnt(4)
	v_pk_add_f32 v[188:189], v[142:143], v[188:189]
	v_max3_f32 v140, v2, s95, v3
	v_max3_f32 v140, v140, v188, v189
	s_waitcnt lgkmcnt(2)
	v_pk_add_f32 v[190:191], v[144:145], v[190:191]
	s_waitcnt lgkmcnt(0)
	v_pk_add_f32 v[192:193], v[146:147], v[192:193]
	v_max3_f32 v140, v140, v190, v191
	v_max3_f32 v243, v140, v192, v193

.LBB0_415:
	v_sub_f32_e32 v2, v2, v242
	v_exp_f32_e32 v246, v2
	v_sub_f32_e32 v2, v3, v242
	v_exp_f32_e32 v241, v2
	v_sub_f32_e32 v2, v188, v242
	v_exp_f32_e32 v243, v2
	v_sub_f32_e32 v2, v189, v242
	v_exp_f32_e32 v244, v2
	v_sub_f32_e32 v2, v190, v242
	v_exp_f32_e32 v245, v2
	v_sub_f32_e32 v2, v191, v242
	v_exp_f32_e32 v247, v2
	v_sub_f32_e32 v2, v192, v242
	v_exp_f32_e32 v190, v2
	v_sub_f32_e32 v2, v193, v242
	v_exp_f32_e32 v191, v2
	s_and_b64 vcc, exec, s[8:9]
	s_mov_b64 s[14:15], -1
	v_cvt_pk_bf16_f32 v140, v246, v241
	v_cvt_pk_bf16_f32 v141, v243, v244
	v_cvt_pk_bf16_f32 v142, v245, v247
	v_cvt_pk_bf16_f32 v143, v190, v191
	s_cbranch_vccnz .LBB0_417
	v_max3_f32 v2, v132, v133, v134
	v_max3_f32 v2, v2, v135, s95
	v_max3_f32 v3, v136, v137, v138
	v_max3_f32 v193, v2, v3, v139
	s_mov_b64 s[14:15], 0
	v_mov_b32_e32 v189, v139
	v_mov_b32_e32 v188, v138
	v_mov_b32_e32 v147, v137
	v_mov_b32_e32 v146, v136
	v_mov_b32_e32 v145, v135
	v_mov_b32_e32 v144, v134
	v_mov_b32_e32 v3, v133
	v_mov_b32_e32 v2, v132

.LBB0_420:
	s_andn2_b64 vcc, exec, s[14:15]
	s_cbranch_vccnz .LBB0_422
	s_add_i32 s14, 0, 0x22800
	v_lshl_add_u32 v2, v192, 2, s14
	v_add_u32_e32 v3, -4, v2
	v_add_u32_e32 v144, -8, v2
	v_add_u32_e32 v145, -12, v2
	v_add_u32_e32 v146, 0xffffffc0, v2
	v_subrev_u32_e32 v147, 0x44, v2
	v_subrev_u32_e32 v188, 0x48, v2
	v_subrev_u32_e32 v189, 0x4c, v2
	v_min_u32_e32 v2, 0x247fc, v2
	v_min_u32_e32 v3, 0x247fc, v3
	v_min_u32_e32 v144, 0x247fc, v144
	v_min_u32_e32 v145, 0x247fc, v145
	v_min_u32_e32 v146, 0x247fc, v146
	v_min_u32_e32 v147, 0x247fc, v147
	v_min_u32_e32 v188, 0x247fc, v188
	v_min_u32_e32 v189, 0x247fc, v189
	ds_read_b32 v2, v2
	ds_read_b32 v3, v3
	ds_read_b32 v144, v144
	ds_read_b32 v145, v145
	ds_read_b32 v146, v146
	ds_read_b32 v147, v147
	ds_read_b32 v188, v188
	ds_read_b32 v189, v189
	s_waitcnt lgkmcnt(6)
	v_pk_add_f32 v[2:3], v[132:133], v[2:3]
	s_waitcnt lgkmcnt(4)
	v_pk_add_f32 v[144:145], v[134:135], v[144:145]
	v_max3_f32 v132, v2, s95, v3
	v_max3_f32 v132, v132, v144, v145
	s_waitcnt lgkmcnt(2)
	v_pk_add_f32 v[146:147], v[136:137], v[146:147]
	s_waitcnt lgkmcnt(0)
	v_pk_add_f32 v[188:189], v[138:139], v[188:189]
	v_max3_f32 v132, v132, v146, v147
	v_max3_f32 v193, v132, v188, v189

; __device__ __forceinline__ void attn_item(const Params& p, unsigned char* lds, int item) {
;     ...
;         for (int ch = 0; ch < 8; ++ch) if (2 * ch < nkt) {
;             f32x4 sA[2], sB[2];
; #pragma unroll
;             for (int k4 = 0; k4 < 2; ++k4) { sA[k4] = (f32x4){0.f, 0.f, 0.f, 0.f}; sB[k4] = (f32x4){0.f, 0.f, 0.f, 0.f};
;                 if (2 * ch + k4 < nkt) { const unsigned char* ka = lds + AT_K + (16 * (2 * ch + k4) + qi) * 272 + 16 * g4;
; #pragma unroll
;                     for (int s = 0; s < 4; ++s) { const bf16x8 a = *(const bf16x8*)(ka + 64 * s);
;                         sA[k4] = __builtin_amdgcn_mfma_f32_16x16x32_bf16(a, bqA[s], sA[k4], 0, 0, 0); sB[k4] = __builtin_amdgcn_mfma_f32_16x16x32_bf16(a, bqB[s], sB[k4], 0, 0, 0); } } }
.LBB0_425:
	ds_read_b128 v[132:135], v206 offset:17408
	ds_read_b128 v[136:139], v206 offset:17472
	s_mov_b64 s[14:15], -1
	s_and_b64 vcc, exec, s[6:7]
	s_waitcnt lgkmcnt(1)
	v_mfma_f32_16x16x32_bf16 v[140:143], v[132:135], v[64:67], 0
	v_mfma_f32_16x16x32_bf16 v[132:135], v[132:135], v[56:59], 0
	s_waitcnt lgkmcnt(0)
	v_mfma_f32_16x16x32_bf16 v[140:143], v[136:139], v[60:63], v[140:143]
	v_mfma_f32_16x16x32_bf16 v[132:135], v[136:139], v[52:55], v[132:135]
	ds_read_b128 v[136:139], v206 offset:17536
	ds_read_b128 v[144:147], v206 offset:17600
	s_waitcnt lgkmcnt(1)
	v_mfma_f32_16x16x32_bf16 v[140:143], v[136:139], v[48:51], v[140:143]
	v_mfma_f32_16x16x32_bf16 v[132:135], v[136:139], v[40:43], v[132:135]
	s_waitcnt lgkmcnt(0)
	v_mfma_f32_16x16x32_bf16 v[140:143], v[144:147], v[44:47], v[140:143]
	v_mfma_f32_16x16x32_bf16 v[132:135], v[144:147], v[36:39], v[132:135]
	ds_read_b128 v[136:139], v206 offset:21760
	ds_read_b128 v[144:147], v206 offset:21824
	s_waitcnt lgkmcnt(1)
	v_mfma_f32_16x16x32_bf16 v[188:191], v[136:139], v[64:67], 0
	v_mfma_f32_16x16x32_bf16 v[136:139], v[136:139], v[56:59], 0
	s_waitcnt lgkmcnt(0)
	v_mfma_f32_16x16x32_bf16 v[188:191], v[144:147], v[60:63], v[188:191]
	v_mfma_f32_16x16x32_bf16 v[136:139], v[144:147], v[52:55], v[136:139]
	ds_read_b128 v[144:147], v206 offset:21888
	ds_read_b128 v[244:247], v206 offset:21952
	s_waitcnt lgkmcnt(1)
	v_mfma_f32_16x16x32_bf16 v[188:191], v[144:147], v[48:51], v[188:191]
	v_mfma_f32_16x16x32_bf16 v[136:139], v[144:147], v[40:43], v[136:139]
	s_waitcnt lgkmcnt(0)
	v_mfma_f32_16x16x32_bf16 v[144:147], v[244:247], v[44:47], v[188:191]
	v_mfma_f32_16x16x32_bf16 v[136:139], v[244:247], v[36:39], v[136:139]
	s_cbranch_vccnz .LBB0_427
	v_max3_f32 v2, v140, v141, v142
	v_max3_f32 v2, v2, v143, s95
	v_max3_f32 v3, v144, v145, v146
	v_max3_f32 v243, v2, v3, v147
	s_mov_b64 s[14:15], 0
	v_mov_b32_e32 v193, v147
	v_mov_b32_e32 v192, v146
	v_mov_b32_e32 v191, v145
	v_mov_b32_e32 v190, v144
	v_mov_b32_e32 v189, v143
	v_mov_b32_e32 v188, v142
	v_mov_b32_e32 v3, v141
	v_mov_b32_e32 v2, v140

; __device__ __forceinline__ void attn_item(const Params& p, unsigned char* lds, int item) {
;     ...
;         for (int ch = 0; ch < 8; ++ch) if (2 * ch < nkt) {
;             f32x4 sA[2], sB[2];
; #pragma unroll
;             for (int k4 = 0; k4 < 2; ++k4) { sA[k4] = (f32x4){0.f, 0.f, 0.f, 0.f}; sB[k4] = (f32x4){0.f, 0.f, 0.f, 0.f};
;                 if (2 * ch + k4 < nkt) { const unsigned char* ka = lds + AT_K + (16 * (2 * ch + k4) + qi) * 272 + 16 * g4;
; #pragma unroll
;                     for (int s = 0; s < 4; ++s) { const bf16x8 a = *(const bf16x8*)(ka + 64 * s);
;                         sA[k4] = __builtin_amdgcn_mfma_f32_16x16x32_bf16(a, bqA[s], sA[k4], 0, 0, 0); sB[k4] = __builtin_amdgcn_mfma_f32_16x16x32_bf16(a, bqB[s], sB[k4], 0, 0, 0); } } }
.LBB0_444:
	ds_read_b128 v[132:135], v206 offset:26112
	ds_read_b128 v[136:139], v206 offset:26176
	s_mov_b64 s[14:15], -1
	s_and_b64 vcc, exec, s[6:7]
	s_waitcnt lgkmcnt(1)
	v_mfma_f32_16x16x32_bf16 v[140:143], v[132:135], v[64:67], 0
	v_mfma_f32_16x16x32_bf16 v[132:135], v[132:135], v[56:59], 0
	s_waitcnt lgkmcnt(0)
	v_mfma_f32_16x16x32_bf16 v[140:143], v[136:139], v[60:63], v[140:143]
	v_mfma_f32_16x16x32_bf16 v[132:135], v[136:139], v[52:55], v[132:135]
	ds_read_b128 v[136:139], v206 offset:26240
	ds_read_b128 v[144:147], v206 offset:26304
	s_waitcnt lgkmcnt(1)
	v_mfma_f32_16x16x32_bf16 v[140:143], v[136:139], v[48:51], v[140:143]
	v_mfma_f32_16x16x32_bf16 v[132:135], v[136:139], v[40:43], v[132:135]
	s_waitcnt lgkmcnt(0)
	v_mfma_f32_16x16x32_bf16 v[140:143], v[144:147], v[44:47], v[140:143]
	v_mfma_f32_16x16x32_bf16 v[132:135], v[144:147], v[36:39], v[132:135]
	ds_read_b128 v[136:139], v206 offset:30464
	ds_read_b128 v[144:147], v206 offset:30528
	s_waitcnt lgkmcnt(1)
	v_mfma_f32_16x16x32_bf16 v[188:191], v[136:139], v[64:67], 0
	v_mfma_f32_16x16x32_bf16 v[136:139], v[136:139], v[56:59], 0
	s_waitcnt lgkmcnt(0)
	v_mfma_f32_16x16x32_bf16 v[188:191], v[144:147], v[60:63], v[188:191]
	v_mfma_f32_16x16x32_bf16 v[136:139], v[144:147], v[52:55], v[136:139]
	ds_read_b128 v[144:147], v206 offset:30592
	ds_read_b128 v[244:247], v206 offset:30656
	s_waitcnt lgkmcnt(1)
	v_mfma_f32_16x16x32_bf16 v[188:191], v[144:147], v[48:51], v[188:191]
	v_mfma_f32_16x16x32_bf16 v[136:139], v[144:147], v[40:43], v[136:139]
	s_waitcnt lgkmcnt(0)
	v_mfma_f32_16x16x32_bf16 v[144:147], v[244:247], v[44:47], v[188:191]
	v_mfma_f32_16x16x32_bf16 v[136:139], v[244:247], v[36:39], v[136:139]
	s_cbranch_vccnz .LBB0_446
	v_max3_f32 v2, v140, v141, v142
	v_max3_f32 v2, v2, v143, s95
	v_max3_f32 v3, v144, v145, v146
	v_max3_f32 v243, v2, v3, v147
	s_mov_b64 s[14:15], 0
	v_mov_b32_e32 v193, v147
	v_mov_b32_e32 v192, v146
	v_mov_b32_e32 v191, v145
	v_mov_b32_e32 v190, v144
	v_mov_b32_e32 v189, v143
	v_mov_b32_e32 v188, v142
	v_mov_b32_e32 v3, v141
	v_mov_b32_e32 v2, v140

; __device__ __forceinline__ void attn_item(const Params& p, unsigned char* lds, int item) {
;     ...
;         for (int ch = 0; ch < 8; ++ch) if (2 * ch < nkt) {
;             f32x4 sA[2], sB[2];
; #pragma unroll
;             for (int k4 = 0; k4 < 2; ++k4) { sA[k4] = (f32x4){0.f, 0.f, 0.f, 0.f}; sB[k4] = (f32x4){0.f, 0.f, 0.f, 0.f};
;                 if (2 * ch + k4 < nkt) { const unsigned char* ka = lds + AT_K + (16 * (2 * ch + k4) + qi) * 272 + 16 * g4;
; #pragma unroll
;                     for (int s = 0; s < 4; ++s) { const bf16x8 a = *(const bf16x8*)(ka + 64 * s);
;                         sA[k4] = __builtin_amdgcn_mfma_f32_16x16x32_bf16(a, bqA[s], sA[k4], 0, 0, 0); sB[k4] = __builtin_amdgcn_mfma_f32_16x16x32_bf16(a, bqB[s], sB[k4], 0, 0, 0); } } }
.LBB0_463:
	ds_read_b128 v[132:135], v206 offset:34816
	ds_read_b128 v[136:139], v206 offset:34880
	s_mov_b64 s[14:15], -1
	s_and_b64 vcc, exec, s[6:7]
	s_waitcnt lgkmcnt(1)
	v_mfma_f32_16x16x32_bf16 v[140:143], v[132:135], v[64:67], 0
	v_mfma_f32_16x16x32_bf16 v[132:135], v[132:135], v[56:59], 0
	s_waitcnt lgkmcnt(0)
	v_mfma_f32_16x16x32_bf16 v[140:143], v[136:139], v[60:63], v[140:143]
	v_mfma_f32_16x16x32_bf16 v[132:135], v[136:139], v[52:55], v[132:135]
	ds_read_b128 v[136:139], v206 offset:34944
	ds_read_b128 v[144:147], v206 offset:35008
	s_waitcnt lgkmcnt(1)
	v_mfma_f32_16x16x32_bf16 v[140:143], v[136:139], v[48:51], v[140:143]
	v_mfma_f32_16x16x32_bf16 v[132:135], v[136:139], v[40:43], v[132:135]
	s_waitcnt lgkmcnt(0)
	v_mfma_f32_16x16x32_bf16 v[140:143], v[144:147], v[44:47], v[140:143]
	v_mfma_f32_16x16x32_bf16 v[132:135], v[144:147], v[36:39], v[132:135]
	ds_read_b128 v[136:139], v206 offset:39168
	ds_read_b128 v[144:147], v206 offset:39232
	s_waitcnt lgkmcnt(1)
	v_mfma_f32_16x16x32_bf16 v[188:191], v[136:139], v[64:67], 0
	v_mfma_f32_16x16x32_bf16 v[136:139], v[136:139], v[56:59], 0
	s_waitcnt lgkmcnt(0)
	v_mfma_f32_16x16x32_bf16 v[188:191], v[144:147], v[60:63], v[188:191]
	v_mfma_f32_16x16x32_bf16 v[136:139], v[144:147], v[52:55], v[136:139]
	ds_read_b128 v[144:147], v206 offset:39296
	ds_read_b128 v[244:247], v206 offset:39360
	s_waitcnt lgkmcnt(1)
	v_mfma_f32_16x16x32_bf16 v[188:191], v[144:147], v[48:51], v[188:191]
	v_mfma_f32_16x16x32_bf16 v[136:139], v[144:147], v[40:43], v[136:139]
	s_waitcnt lgkmcnt(0)
	v_mfma_f32_16x16x32_bf16 v[144:147], v[244:247], v[44:47], v[188:191]
	v_mfma_f32_16x16x32_bf16 v[136:139], v[244:247], v[36:39], v[136:139]
	s_cbranch_vccnz .LBB0_465
	v_max3_f32 v2, v140, v141, v142
	v_max3_f32 v2, v2, v143, s95
	v_max3_f32 v3, v144, v145, v146
	v_max3_f32 v243, v2, v3, v147
	s_mov_b64 s[14:15], 0
	v_mov_b32_e32 v193, v147
	v_mov_b32_e32 v192, v146
	v_mov_b32_e32 v191, v145
	v_mov_b32_e32 v190, v144
	v_mov_b32_e32 v189, v143
	v_mov_b32_e32 v188, v142
	v_mov_b32_e32 v3, v141
	v_mov_b32_e32 v2, v140

; __device__ __forceinline__ void attn_item(const Params& p, unsigned char* lds, int item) {
;     ...
;         for (int ch = 0; ch < 8; ++ch) if (2 * ch < nkt) {
;             f32x4 sA[2], sB[2];
; #pragma unroll
;             for (int k4 = 0; k4 < 2; ++k4) { sA[k4] = (f32x4){0.f, 0.f, 0.f, 0.f}; sB[k4] = (f32x4){0.f, 0.f, 0.f, 0.f};
;                 if (2 * ch + k4 < nkt) { const unsigned char* ka = lds + AT_K + (16 * (2 * ch + k4) + qi) * 272 + 16 * g4;
; #pragma unroll
;                     for (int s = 0; s < 4; ++s) { const bf16x8 a = *(const bf16x8*)(ka + 64 * s);
;                         sA[k4] = __builtin_amdgcn_mfma_f32_16x16x32_bf16(a, bqA[s], sA[k4], 0, 0, 0); sB[k4] = __builtin_amdgcn_mfma_f32_16x16x32_bf16(a, bqB[s], sB[k4], 0, 0, 0); } } }
.LBB0_482:
	ds_read_b128 v[132:135], v206 offset:43520
	ds_read_b128 v[136:139], v206 offset:43584
	s_mov_b64 s[14:15], -1
	s_and_b64 vcc, exec, s[6:7]
	s_waitcnt lgkmcnt(1)
	v_mfma_f32_16x16x32_bf16 v[140:143], v[132:135], v[64:67], 0
	v_mfma_f32_16x16x32_bf16 v[132:135], v[132:135], v[56:59], 0
	s_waitcnt lgkmcnt(0)
	v_mfma_f32_16x16x32_bf16 v[140:143], v[136:139], v[60:63], v[140:143]
	v_mfma_f32_16x16x32_bf16 v[132:135], v[136:139], v[52:55], v[132:135]
	ds_read_b128 v[136:139], v206 offset:43648
	ds_read_b128 v[144:147], v206 offset:43712
	s_waitcnt lgkmcnt(1)
	v_mfma_f32_16x16x32_bf16 v[140:143], v[136:139], v[48:51], v[140:143]
	v_mfma_f32_16x16x32_bf16 v[132:135], v[136:139], v[40:43], v[132:135]
	s_waitcnt lgkmcnt(0)
	v_mfma_f32_16x16x32_bf16 v[140:143], v[144:147], v[44:47], v[140:143]
	v_mfma_f32_16x16x32_bf16 v[132:135], v[144:147], v[36:39], v[132:135]
	ds_read_b128 v[136:139], v206 offset:47872
	ds_read_b128 v[144:147], v206 offset:47936
	s_waitcnt lgkmcnt(1)
	v_mfma_f32_16x16x32_bf16 v[188:191], v[136:139], v[64:67], 0
	v_mfma_f32_16x16x32_bf16 v[136:139], v[136:139], v[56:59], 0
	s_waitcnt lgkmcnt(0)
	v_mfma_f32_16x16x32_bf16 v[188:191], v[144:147], v[60:63], v[188:191]
	v_mfma_f32_16x16x32_bf16 v[136:139], v[144:147], v[52:55], v[136:139]
	ds_read_b128 v[144:147], v206 offset:48000
	ds_read_b128 v[244:247], v206 offset:48064
	s_waitcnt lgkmcnt(1)
	v_mfma_f32_16x16x32_bf16 v[188:191], v[144:147], v[48:51], v[188:191]
	v_mfma_f32_16x16x32_bf16 v[136:139], v[144:147], v[40:43], v[136:139]
	s_waitcnt lgkmcnt(0)
	v_mfma_f32_16x16x32_bf16 v[144:147], v[244:247], v[44:47], v[188:191]
	v_mfma_f32_16x16x32_bf16 v[136:139], v[244:247], v[36:39], v[136:139]
	s_cbranch_vccnz .LBB0_484
	v_max3_f32 v2, v140, v141, v142
	v_max3_f32 v2, v2, v143, s95
	v_max3_f32 v3, v144, v145, v146
	v_max3_f32 v243, v2, v3, v147
	s_mov_b64 s[14:15], 0
	v_mov_b32_e32 v193, v147
	v_mov_b32_e32 v192, v146
	v_mov_b32_e32 v191, v145
	v_mov_b32_e32 v190, v144
	v_mov_b32_e32 v189, v143
	v_mov_b32_e32 v188, v142
	v_mov_b32_e32 v3, v141
	v_mov_b32_e32 v2, v140

; __device__ __forceinline__ void attn_item(const Params& p, unsigned char* lds, int item) {
;     ...
;         for (int ch = 0; ch < 8; ++ch) if (2 * ch < nkt) {
;             f32x4 sA[2], sB[2];
; #pragma unroll
;             for (int k4 = 0; k4 < 2; ++k4) { sA[k4] = (f32x4){0.f, 0.f, 0.f, 0.f}; sB[k4] = (f32x4){0.f, 0.f, 0.f, 0.f};
;                 if (2 * ch + k4 < nkt) { const unsigned char* ka = lds + AT_K + (16 * (2 * ch + k4) + qi) * 272 + 16 * g4;
; #pragma unroll
;                     for (int s = 0; s < 4; ++s) { const bf16x8 a = *(const bf16x8*)(ka + 64 * s);
;                         sA[k4] = __builtin_amdgcn_mfma_f32_16x16x32_bf16(a, bqA[s], sA[k4], 0, 0, 0); sB[k4] = __builtin_amdgcn_mfma_f32_16x16x32_bf16(a, bqB[s], sB[k4], 0, 0, 0); } } }
.LBB0_501:
	ds_read_b128 v[132:135], v206 offset:52224
	ds_read_b128 v[136:139], v206 offset:52288
	s_mov_b64 s[14:15], -1
	s_and_b64 vcc, exec, s[6:7]
	s_waitcnt lgkmcnt(1)
	v_mfma_f32_16x16x32_bf16 v[140:143], v[132:135], v[64:67], 0
	v_mfma_f32_16x16x32_bf16 v[132:135], v[132:135], v[56:59], 0
	s_waitcnt lgkmcnt(0)
	v_mfma_f32_16x16x32_bf16 v[140:143], v[136:139], v[60:63], v[140:143]
	v_mfma_f32_16x16x32_bf16 v[132:135], v[136:139], v[52:55], v[132:135]
	ds_read_b128 v[136:139], v206 offset:52352
	ds_read_b128 v[144:147], v206 offset:52416
	s_waitcnt lgkmcnt(1)
	v_mfma_f32_16x16x32_bf16 v[140:143], v[136:139], v[48:51], v[140:143]
	v_mfma_f32_16x16x32_bf16 v[132:135], v[136:139], v[40:43], v[132:135]
	s_waitcnt lgkmcnt(0)
	v_mfma_f32_16x16x32_bf16 v[140:143], v[144:147], v[44:47], v[140:143]
	v_mfma_f32_16x16x32_bf16 v[132:135], v[144:147], v[36:39], v[132:135]
	ds_read_b128 v[136:139], v206 offset:56576
	ds_read_b128 v[144:147], v206 offset:56640
	s_waitcnt lgkmcnt(1)
	v_mfma_f32_16x16x32_bf16 v[188:191], v[136:139], v[64:67], 0
	v_mfma_f32_16x16x32_bf16 v[136:139], v[136:139], v[56:59], 0
	s_waitcnt lgkmcnt(0)
	v_mfma_f32_16x16x32_bf16 v[188:191], v[144:147], v[60:63], v[188:191]
	v_mfma_f32_16x16x32_bf16 v[136:139], v[144:147], v[52:55], v[136:139]
	ds_read_b128 v[144:147], v206 offset:56704
	ds_read_b128 v[244:247], v206 offset:56768
	s_waitcnt lgkmcnt(1)
	v_mfma_f32_16x16x32_bf16 v[188:191], v[144:147], v[48:51], v[188:191]
	v_mfma_f32_16x16x32_bf16 v[136:139], v[144:147], v[40:43], v[136:139]
	s_waitcnt lgkmcnt(0)
	v_mfma_f32_16x16x32_bf16 v[144:147], v[244:247], v[44:47], v[188:191]
	v_mfma_f32_16x16x32_bf16 v[136:139], v[244:247], v[36:39], v[136:139]
	s_cbranch_vccnz .LBB0_503
	v_max3_f32 v2, v140, v141, v142
	v_max3_f32 v2, v2, v143, s95
	v_max3_f32 v3, v144, v145, v146
	v_max3_f32 v243, v2, v3, v147
	s_mov_b64 s[14:15], 0
	v_mov_b32_e32 v193, v147
	v_mov_b32_e32 v192, v146
	v_mov_b32_e32 v191, v145
	v_mov_b32_e32 v190, v144
	v_mov_b32_e32 v189, v143
	v_mov_b32_e32 v188, v142
	v_mov_b32_e32 v3, v141
	v_mov_b32_e32 v2, v140

; __device__ __forceinline__ void attn_item(const Params& p, unsigned char* lds, int item) {
;     ...
;         for (int ch = 0; ch < 8; ++ch) if (2 * ch < nkt) {
;             f32x4 sA[2], sB[2];
; #pragma unroll
;             for (int k4 = 0; k4 < 2; ++k4) { sA[k4] = (f32x4){0.f, 0.f, 0.f, 0.f}; sB[k4] = (f32x4){0.f, 0.f, 0.f, 0.f};
;                 if (2 * ch + k4 < nkt) { const unsigned char* ka = lds + AT_K + (16 * (2 * ch + k4) + qi) * 272 + 16 * g4;
; #pragma unroll
;                     for (int s = 0; s < 4; ++s) { const bf16x8 a = *(const bf16x8*)(ka + 64 * s);
;                         sA[k4] = __builtin_amdgcn_mfma_f32_16x16x32_bf16(a, bqA[s], sA[k4], 0, 0, 0); sB[k4] = __builtin_amdgcn_mfma_f32_16x16x32_bf16(a, bqB[s], sB[k4], 0, 0, 0); } } }
.LBB0_520:
	ds_read_b128 v[132:135], v206 offset:60928
	ds_read_b128 v[136:139], v206 offset:60992
	s_mov_b64 s[10:11], -1
	s_and_b64 vcc, exec, s[6:7]
	s_waitcnt lgkmcnt(1)
	v_mfma_f32_16x16x32_bf16 v[140:143], v[132:135], v[64:67], 0
	v_mfma_f32_16x16x32_bf16 v[132:135], v[132:135], v[56:59], 0
	s_waitcnt lgkmcnt(0)
	v_mfma_f32_16x16x32_bf16 v[140:143], v[136:139], v[60:63], v[140:143]
	v_mfma_f32_16x16x32_bf16 v[132:135], v[136:139], v[52:55], v[132:135]
	ds_read_b128 v[136:139], v206 offset:61056
	ds_read_b128 v[144:147], v206 offset:61120
	s_waitcnt lgkmcnt(1)
	v_mfma_f32_16x16x32_bf16 v[140:143], v[136:139], v[48:51], v[140:143]
	v_mfma_f32_16x16x32_bf16 v[132:135], v[136:139], v[40:43], v[132:135]
	s_waitcnt lgkmcnt(0)
	v_mfma_f32_16x16x32_bf16 v[136:139], v[144:147], v[44:47], v[140:143]
	v_mfma_f32_16x16x32_bf16 v[132:135], v[144:147], v[36:39], v[132:135]
	s_nop 3
	ds_read_b128 v[140:143], v206 offset:65280
	ds_read_b128 v[144:147], v206 offset:65344
	s_waitcnt lgkmcnt(1)
	v_mfma_f32_16x16x32_bf16 v[64:67], v[140:143], v[64:67], 0
	v_mfma_f32_16x16x32_bf16 v[56:59], v[140:143], v[56:59], 0
	s_waitcnt lgkmcnt(0)
	v_mfma_f32_16x16x32_bf16 v[60:63], v[144:147], v[60:63], v[64:67]
	v_mfma_f32_16x16x32_bf16 v[52:55], v[144:147], v[52:55], v[56:59]
	s_nop 4
	ds_read_b128 v[56:59], v206 offset:65408
	ds_read_b128 v[64:67], v206 offset:65472
	s_waitcnt lgkmcnt(1)
	v_mfma_f32_16x16x32_bf16 v[48:51], v[56:59], v[48:51], v[60:63]
	v_mfma_f32_16x16x32_bf16 v[52:55], v[56:59], v[40:43], v[52:55]
	s_waitcnt lgkmcnt(0)
	v_mfma_f32_16x16x32_bf16 v[40:43], v[64:67], v[44:47], v[48:51]
	v_mfma_f32_16x16x32_bf16 v[36:39], v[64:67], v[36:39], v[52:55]
	s_cbranch_vccnz .LBB0_522
	v_max3_f32 v2, v136, v137, v138
	v_max3_f32 v2, v2, v139, s95
	v_max3_f32 v3, v40, v41, v42
	v_max3_f32 v50, v2, v3, v43
	s_mov_b64 s[10:11], 0
	v_mov_b32_e32 v45, v43
	v_mov_b32_e32 v44, v42
	v_mov_b32_e32 v3, v41
	v_mov_b32_e32 v2, v40
	v_mov_b32_e32 v47, v139
	v_mov_b32_e32 v46, v138
	v_mov_b32_e32 v49, v137
	v_mov_b32_e32 v48, v136

.LBB0_529:
	v_sub_f32_e32 v40, v48, v0
	v_sub_f32_e32 v2, v2, v0
	v_exp_f32_e32 v56, v40
	v_sub_f32_e32 v40, v49, v0
	v_exp_f32_e32 v55, v2
	v_sub_f32_e32 v2, v3, v0
	v_exp_f32_e32 v50, v40
	v_sub_f32_e32 v40, v46, v0
	v_exp_f32_e32 v57, v2
	v_sub_f32_e32 v2, v44, v0
	v_exp_f32_e32 v52, v40
	v_sub_f32_e32 v40, v47, v0
	v_exp_f32_e32 v51, v2
	v_sub_f32_e32 v2, v45, v0
	v_exp_f32_e32 v54, v40
	v_exp_f32_e32 v53, v2
	s_and_b64 vcc, exec, s[8:9]
	s_mov_b64 s[6:7], -1
	v_cvt_pk_bf16_f32 v40, v56, v50
	v_cvt_pk_bf16_f32 v41, v52, v54
	v_cvt_pk_bf16_f32 v42, v55, v57
	v_cvt_pk_bf16_f32 v43, v51, v53
	s_cbranch_vccnz .LBB0_531
	v_max3_f32 v2, v132, v133, v134
	v_max3_f32 v2, v2, v135, s95
	v_max3_f32 v3, v36, v37, v38
	v_max3_f32 v59, v2, v3, v39
	s_mov_b64 s[6:7], 0
	v_mov_b32_e32 v3, v39
	v_mov_b32_e32 v2, v38
	v_mov_b32_e32 v45, v37
	v_mov_b32_e32 v44, v36
	v_mov_b32_e32 v47, v135
	v_mov_b32_e32 v46, v134
	v_mov_b32_e32 v49, v133
	v_mov_b32_e32 v48, v132
